# P9 final-norm f32 stores: quads exchanged across the 4 fq lanes (permlane16+32 swap) so each dwordx4 store writes 64 contiguous bytes per row instead of 16-byte runs
# baseline (speedup 1.0000x reference)
.LBB0_1449:
	global_load_dword v171, v[128:129], off sc1
	global_load_dword v174, v[128:129], off offset:64 sc1
	global_load_dword v175, v[128:129], off offset:128 sc1
	global_load_dword v176, v[128:129], off offset:192 sc1
	global_load_dword v177, v[128:129], off offset:512 sc1
	global_load_dword v184, v[128:129], off offset:576 sc1
	global_load_dword v185, v[128:129], off offset:640 sc1
	global_load_dword v186, v[128:129], off offset:704 sc1
	v_lshl_or_b32 v128, s77, 8, v180
	v_ashrrev_i32_e32 v129, 31, v128
	v_lshlrev_b64 v[168:169], 2, v[128:129]
	v_lshl_add_u64 v[128:129], s[24:25], 0, v[168:169]
	global_load_dwordx4 v[140:143], v[128:129], off
	global_load_dwordx4 v[136:139], v[128:129], off offset:16
	global_load_dwordx4 v[132:135], v[128:129], off offset:512
	s_waitcnt lgkmcnt(0)
	global_load_dwordx4 v[128:131], v[128:129], off offset:528
	v_lshlrev_b64 v[162:163], 12, v[160:161]
	v_lshl_add_u64 v[162:163], s[26:27], 0, v[162:163]
	v_lshl_add_u64 v[164:165], v[162:163], 0, v[168:169]
	v_and_b32_e32 v170, 24, v180
	v_lshlrev_b32_e32 v170, 1, v170
	v_sub_co_u32_e32 v164, vcc, v164, v170
	v_subbrev_co_u32_e32 v165, vcc, 0, v165, vcc
	s_waitcnt vmcnt(4)
	v_fmamk_f32 v161, v171, 0x3a800000, v183
	v_fmamk_f32 v162, v174, 0x3a800000, v183
	v_fmamk_f32 v163, v175, 0x3a800000, v183
	v_fmamk_f32 v166, v176, 0x3a800000, v183
	v_fmamk_f32 v167, v177, 0x3a800000, v183
	v_fmamk_f32 v170, v184, 0x3a800000, v183
	v_fmamk_f32 v194, v185, 0x3a800000, v183
	v_fmamk_f32 v195, v186, 0x3a800000, v183
	v_rsq_f32_e32 v161, v161
	v_rsq_f32_e32 v162, v162
	v_rsq_f32_e32 v163, v163
	v_rsq_f32_e32 v166, v166
	v_rsq_f32_e32 v167, v167
	v_rsq_f32_e32 v170, v170
	v_rsq_f32_e32 v194, v194
	v_rsq_f32_e32 v195, v195
	s_nop 0
	v_mul_f32_e32 v172, 0.5, v161
	v_mul_f32_e32 v174, 0.5, v162
	v_mul_f32_e32 v176, 0.5, v163
	v_mul_f32_e32 v184, 0.5, v166
	v_mul_f32_e32 v186, 0.5, v167
	v_mul_f32_e32 v188, 0.5, v170
	v_mul_f32_e32 v190, 0.5, v194
	v_mul_f32_e32 v192, 0.5, v195
	s_waitcnt vmcnt(0)
	v_pk_mul_f32 v[28:29], v[28:29], v[172:173] op_sel_hi:[1,0]
	v_pk_mul_f32 v[30:31], v[30:31], v[172:173] op_sel_hi:[1,0]
	v_pk_mul_f32 v[36:37], v[36:37], v[172:173] op_sel_hi:[1,0]
	v_pk_mul_f32 v[38:39], v[38:39], v[172:173] op_sel_hi:[1,0]
	v_pk_mul_f32 v[28:29], v[28:29], v[140:141]
	v_pk_mul_f32 v[30:31], v[30:31], v[142:143]
	v_pk_mul_f32 v[36:37], v[36:37], v[136:137]
	v_pk_mul_f32 v[38:39], v[38:39], v[138:139]
	s_nop 1
	v_permlane16_swap_b32_e32 v28, v36
	v_permlane16_swap_b32_e32 v29, v37
	v_permlane16_swap_b32_e32 v30, v38
	v_permlane16_swap_b32_e32 v31, v39
	s_nop 1
	v_permlane32_swap_b32_e32 v28, v36
	v_permlane32_swap_b32_e32 v29, v37
	v_permlane32_swap_b32_e32 v30, v38
	v_permlane32_swap_b32_e32 v31, v39
	s_nop 1
	global_store_dwordx4 v[164:165], v[28:31], off
	global_store_dwordx4 v[164:165], v[36:39], off offset:64
	v_pk_mul_f32 v[104:105], v[104:105], v[172:173] op_sel_hi:[1,0]
	v_pk_mul_f32 v[106:107], v[106:107], v[172:173] op_sel_hi:[1,0]
	v_pk_mul_f32 v[108:109], v[108:109], v[172:173] op_sel_hi:[1,0]
	v_pk_mul_f32 v[110:111], v[110:111], v[172:173] op_sel_hi:[1,0]
	v_pk_mul_f32 v[104:105], v[104:105], v[132:133]
	v_pk_mul_f32 v[106:107], v[106:107], v[134:135]
	v_pk_mul_f32 v[108:109], v[108:109], v[128:129]
	v_pk_mul_f32 v[110:111], v[110:111], v[130:131]
	s_nop 1
	v_permlane16_swap_b32_e32 v104, v108
	v_permlane16_swap_b32_e32 v105, v109
	v_permlane16_swap_b32_e32 v106, v110
	v_permlane16_swap_b32_e32 v107, v111
	s_nop 1
	v_permlane32_swap_b32_e32 v104, v108
	v_permlane32_swap_b32_e32 v105, v109
	v_permlane32_swap_b32_e32 v106, v110
	v_permlane32_swap_b32_e32 v107, v111
	s_nop 1
	global_store_dwordx4 v[164:165], v[104:107], off offset:512
	global_store_dwordx4 v[164:165], v[108:111], off offset:576
	v_add_co_u32_e32 v196, vcc, 0x10000, v164
	v_addc_co_u32_e32 v197, vcc, 0, v165, vcc
	v_pk_mul_f32 v[44:45], v[44:45], v[174:175] op_sel_hi:[1,0]
	v_pk_mul_f32 v[46:47], v[46:47], v[174:175] op_sel_hi:[1,0]
	v_pk_mul_f32 v[52:53], v[52:53], v[174:175] op_sel_hi:[1,0]
	v_pk_mul_f32 v[54:55], v[54:55], v[174:175] op_sel_hi:[1,0]
	v_pk_mul_f32 v[44:45], v[44:45], v[140:141]
	v_pk_mul_f32 v[46:47], v[46:47], v[142:143]
	v_pk_mul_f32 v[52:53], v[52:53], v[136:137]
	v_pk_mul_f32 v[54:55], v[54:55], v[138:139]
	s_nop 1
	v_permlane16_swap_b32_e32 v44, v52
	v_permlane16_swap_b32_e32 v45, v53
	v_permlane16_swap_b32_e32 v46, v54
	v_permlane16_swap_b32_e32 v47, v55
	s_nop 1
	v_permlane32_swap_b32_e32 v44, v52
	v_permlane32_swap_b32_e32 v45, v53
	v_permlane32_swap_b32_e32 v46, v54
	v_permlane32_swap_b32_e32 v47, v55
	s_nop 1
	global_store_dwordx4 v[196:197], v[44:47], off
	global_store_dwordx4 v[196:197], v[52:55], off offset:64
	v_pk_mul_f32 v[112:113], v[112:113], v[174:175] op_sel_hi:[1,0]
	v_pk_mul_f32 v[114:115], v[114:115], v[174:175] op_sel_hi:[1,0]
	v_pk_mul_f32 v[124:125], v[124:125], v[174:175] op_sel_hi:[1,0]
	v_pk_mul_f32 v[126:127], v[126:127], v[174:175] op_sel_hi:[1,0]
	v_pk_mul_f32 v[112:113], v[112:113], v[132:133]
	v_pk_mul_f32 v[114:115], v[114:115], v[134:135]
	v_pk_mul_f32 v[124:125], v[124:125], v[128:129]
	v_pk_mul_f32 v[126:127], v[126:127], v[130:131]
	s_nop 1
	v_permlane16_swap_b32_e32 v112, v124
	v_permlane16_swap_b32_e32 v113, v125
	v_permlane16_swap_b32_e32 v114, v126
	v_permlane16_swap_b32_e32 v115, v127
	s_nop 1
	v_permlane32_swap_b32_e32 v112, v124
	v_permlane32_swap_b32_e32 v113, v125
	v_permlane32_swap_b32_e32 v114, v126
	v_permlane32_swap_b32_e32 v115, v127
	s_nop 1
	global_store_dwordx4 v[196:197], v[112:115], off offset:512
	global_store_dwordx4 v[196:197], v[124:127], off offset:576
	v_add_co_u32_e32 v196, vcc, 0x20000, v164
	v_addc_co_u32_e32 v197, vcc, 0, v165, vcc
	v_pk_mul_f32 v[32:33], v[32:33], v[176:177] op_sel_hi:[1,0]
	v_pk_mul_f32 v[34:35], v[34:35], v[176:177] op_sel_hi:[1,0]
	v_pk_mul_f32 v[24:25], v[24:25], v[176:177] op_sel_hi:[1,0]
	v_pk_mul_f32 v[26:27], v[26:27], v[176:177] op_sel_hi:[1,0]
	v_pk_mul_f32 v[32:33], v[32:33], v[140:141]
	v_pk_mul_f32 v[34:35], v[34:35], v[142:143]
	v_pk_mul_f32 v[24:25], v[24:25], v[136:137]
	v_pk_mul_f32 v[26:27], v[26:27], v[138:139]
	s_nop 1
	v_permlane16_swap_b32_e32 v32, v24
	v_permlane16_swap_b32_e32 v33, v25
	v_permlane16_swap_b32_e32 v34, v26
	v_permlane16_swap_b32_e32 v35, v27
	s_nop 1
	v_permlane32_swap_b32_e32 v32, v24
	v_permlane32_swap_b32_e32 v33, v25
	v_permlane32_swap_b32_e32 v34, v26
	v_permlane32_swap_b32_e32 v35, v27
	s_nop 1
	global_store_dwordx4 v[196:197], v[32:35], off
	global_store_dwordx4 v[196:197], v[24:27], off offset:64
	v_pk_mul_f32 v[88:89], v[88:89], v[176:177] op_sel_hi:[1,0]
	v_pk_mul_f32 v[90:91], v[90:91], v[176:177] op_sel_hi:[1,0]
	v_pk_mul_f32 v[92:93], v[92:93], v[176:177] op_sel_hi:[1,0]
	v_pk_mul_f32 v[94:95], v[94:95], v[176:177] op_sel_hi:[1,0]
	v_pk_mul_f32 v[88:89], v[88:89], v[132:133]
	v_pk_mul_f32 v[90:91], v[90:91], v[134:135]
	v_pk_mul_f32 v[92:93], v[92:93], v[128:129]
	v_pk_mul_f32 v[94:95], v[94:95], v[130:131]
	s_nop 1
	v_permlane16_swap_b32_e32 v88, v92
	v_permlane16_swap_b32_e32 v89, v93
	v_permlane16_swap_b32_e32 v90, v94
	v_permlane16_swap_b32_e32 v91, v95
	s_nop 1
	v_permlane32_swap_b32_e32 v88, v92
	v_permlane32_swap_b32_e32 v89, v93
	v_permlane32_swap_b32_e32 v90, v94
	v_permlane32_swap_b32_e32 v91, v95
	s_nop 1
	global_store_dwordx4 v[196:197], v[88:91], off offset:512
	global_store_dwordx4 v[196:197], v[92:95], off offset:576
	v_add_co_u32_e32 v196, vcc, 0x30000, v164
	v_addc_co_u32_e32 v197, vcc, 0, v165, vcc
	v_pk_mul_f32 v[12:13], v[12:13], v[184:185] op_sel_hi:[1,0]
	v_pk_mul_f32 v[14:15], v[14:15], v[184:185] op_sel_hi:[1,0]
	v_pk_mul_f32 v[8:9], v[8:9], v[184:185] op_sel_hi:[1,0]
	v_pk_mul_f32 v[10:11], v[10:11], v[184:185] op_sel_hi:[1,0]
	v_pk_mul_f32 v[12:13], v[12:13], v[140:141]
	v_pk_mul_f32 v[14:15], v[14:15], v[142:143]
	v_pk_mul_f32 v[8:9], v[8:9], v[136:137]
	v_pk_mul_f32 v[10:11], v[10:11], v[138:139]
	s_nop 1
	v_permlane16_swap_b32_e32 v12, v8
	v_permlane16_swap_b32_e32 v13, v9
	v_permlane16_swap_b32_e32 v14, v10
	v_permlane16_swap_b32_e32 v15, v11
	s_nop 1
	v_permlane32_swap_b32_e32 v12, v8
	v_permlane32_swap_b32_e32 v13, v9
	v_permlane32_swap_b32_e32 v14, v10
	v_permlane32_swap_b32_e32 v15, v11
	s_nop 1
	global_store_dwordx4 v[196:197], v[12:15], off
	global_store_dwordx4 v[196:197], v[8:11], off offset:64
	v_pk_mul_f32 v[68:69], v[68:69], v[184:185] op_sel_hi:[1,0]
	v_pk_mul_f32 v[70:71], v[70:71], v[184:185] op_sel_hi:[1,0]
	v_pk_mul_f32 v[76:77], v[76:77], v[184:185] op_sel_hi:[1,0]
	v_pk_mul_f32 v[78:79], v[78:79], v[184:185] op_sel_hi:[1,0]
	v_pk_mul_f32 v[68:69], v[68:69], v[132:133]
	v_pk_mul_f32 v[70:71], v[70:71], v[134:135]
	v_pk_mul_f32 v[76:77], v[76:77], v[128:129]
	v_pk_mul_f32 v[78:79], v[78:79], v[130:131]
	s_nop 1
	v_permlane16_swap_b32_e32 v68, v76
	v_permlane16_swap_b32_e32 v69, v77
	v_permlane16_swap_b32_e32 v70, v78
	v_permlane16_swap_b32_e32 v71, v79
	s_nop 1
	v_permlane32_swap_b32_e32 v68, v76
	v_permlane32_swap_b32_e32 v69, v77
	v_permlane32_swap_b32_e32 v70, v78
	v_permlane32_swap_b32_e32 v71, v79
	s_nop 1
	global_store_dwordx4 v[196:197], v[68:71], off offset:512
	global_store_dwordx4 v[196:197], v[76:79], off offset:576
	v_add_co_u32_e32 v196, vcc, 0x80000, v164
	v_addc_co_u32_e32 v197, vcc, 0, v165, vcc
	v_pk_mul_f32 v[72:73], v[72:73], v[186:187] op_sel_hi:[1,0]
	v_pk_mul_f32 v[74:75], v[74:75], v[186:187] op_sel_hi:[1,0]
	v_pk_mul_f32 v[64:65], v[64:65], v[186:187] op_sel_hi:[1,0]
	v_pk_mul_f32 v[66:67], v[66:67], v[186:187] op_sel_hi:[1,0]
	v_pk_mul_f32 v[72:73], v[72:73], v[140:141]
	v_pk_mul_f32 v[74:75], v[74:75], v[142:143]
	v_pk_mul_f32 v[64:65], v[64:65], v[136:137]
	v_pk_mul_f32 v[66:67], v[66:67], v[138:139]
	s_nop 1
	v_permlane16_swap_b32_e32 v72, v64
	v_permlane16_swap_b32_e32 v73, v65
	v_permlane16_swap_b32_e32 v74, v66
	v_permlane16_swap_b32_e32 v75, v67
	s_nop 1
	v_permlane32_swap_b32_e32 v72, v64
	v_permlane32_swap_b32_e32 v73, v65
	v_permlane32_swap_b32_e32 v74, v66
	v_permlane32_swap_b32_e32 v75, v67
	s_nop 1
	global_store_dwordx4 v[196:197], v[72:75], off
	global_store_dwordx4 v[196:197], v[64:67], off offset:64
	v_pk_mul_f32 v[116:117], v[116:117], v[186:187] op_sel_hi:[1,0]
	v_pk_mul_f32 v[118:119], v[118:119], v[186:187] op_sel_hi:[1,0]
	v_pk_mul_f32 v[120:121], v[120:121], v[186:187] op_sel_hi:[1,0]
	v_pk_mul_f32 v[122:123], v[122:123], v[186:187] op_sel_hi:[1,0]
	v_pk_mul_f32 v[116:117], v[116:117], v[132:133]
	v_pk_mul_f32 v[118:119], v[118:119], v[134:135]
	v_pk_mul_f32 v[120:121], v[120:121], v[128:129]
	v_pk_mul_f32 v[122:123], v[122:123], v[130:131]
	s_nop 1
	v_permlane16_swap_b32_e32 v116, v120
	v_permlane16_swap_b32_e32 v117, v121
	v_permlane16_swap_b32_e32 v118, v122
	v_permlane16_swap_b32_e32 v119, v123
	s_nop 1
	v_permlane32_swap_b32_e32 v116, v120
	v_permlane32_swap_b32_e32 v117, v121
	v_permlane32_swap_b32_e32 v118, v122
	v_permlane32_swap_b32_e32 v119, v123
	s_nop 1
	global_store_dwordx4 v[196:197], v[116:119], off offset:512
	global_store_dwordx4 v[196:197], v[120:123], off offset:576
	v_add_co_u32_e32 v196, vcc, 0x90000, v164
	v_addc_co_u32_e32 v197, vcc, 0, v165, vcc
	v_pk_mul_f32 v[48:49], v[48:49], v[188:189] op_sel_hi:[1,0]
	v_pk_mul_f32 v[50:51], v[50:51], v[188:189] op_sel_hi:[1,0]
	v_pk_mul_f32 v[40:41], v[40:41], v[188:189] op_sel_hi:[1,0]
	v_pk_mul_f32 v[42:43], v[42:43], v[188:189] op_sel_hi:[1,0]
	v_pk_mul_f32 v[48:49], v[48:49], v[140:141]
	v_pk_mul_f32 v[50:51], v[50:51], v[142:143]
	v_pk_mul_f32 v[40:41], v[40:41], v[136:137]
	v_pk_mul_f32 v[42:43], v[42:43], v[138:139]
	s_nop 1
	v_permlane16_swap_b32_e32 v48, v40
	v_permlane16_swap_b32_e32 v49, v41
	v_permlane16_swap_b32_e32 v50, v42
	v_permlane16_swap_b32_e32 v51, v43
	s_nop 1
	v_permlane32_swap_b32_e32 v48, v40
	v_permlane32_swap_b32_e32 v49, v41
	v_permlane32_swap_b32_e32 v50, v42
	v_permlane32_swap_b32_e32 v51, v43
	s_nop 1
	global_store_dwordx4 v[196:197], v[48:51], off
	global_store_dwordx4 v[196:197], v[40:43], off offset:64
	v_pk_mul_f32 v[96:97], v[96:97], v[188:189] op_sel_hi:[1,0]
	v_pk_mul_f32 v[98:99], v[98:99], v[188:189] op_sel_hi:[1,0]
	v_pk_mul_f32 v[100:101], v[100:101], v[188:189] op_sel_hi:[1,0]
	v_pk_mul_f32 v[102:103], v[102:103], v[188:189] op_sel_hi:[1,0]
	v_pk_mul_f32 v[96:97], v[96:97], v[132:133]
	v_pk_mul_f32 v[98:99], v[98:99], v[134:135]
	v_pk_mul_f32 v[100:101], v[100:101], v[128:129]
	v_pk_mul_f32 v[102:103], v[102:103], v[130:131]
	s_nop 1
	v_permlane16_swap_b32_e32 v96, v100
	v_permlane16_swap_b32_e32 v97, v101
	v_permlane16_swap_b32_e32 v98, v102
	v_permlane16_swap_b32_e32 v99, v103
	s_nop 1
	v_permlane32_swap_b32_e32 v96, v100
	v_permlane32_swap_b32_e32 v97, v101
	v_permlane32_swap_b32_e32 v98, v102
	v_permlane32_swap_b32_e32 v99, v103
	s_nop 1
	global_store_dwordx4 v[196:197], v[96:99], off offset:512
	global_store_dwordx4 v[196:197], v[100:103], off offset:576
	v_add_co_u32_e32 v196, vcc, 0xa0000, v164
	v_addc_co_u32_e32 v197, vcc, 0, v165, vcc
	v_pk_mul_f32 v[20:21], v[20:21], v[190:191] op_sel_hi:[1,0]
	v_pk_mul_f32 v[22:23], v[22:23], v[190:191] op_sel_hi:[1,0]
	v_pk_mul_f32 v[16:17], v[16:17], v[190:191] op_sel_hi:[1,0]
	v_pk_mul_f32 v[18:19], v[18:19], v[190:191] op_sel_hi:[1,0]
	v_pk_mul_f32 v[20:21], v[20:21], v[140:141]
	v_pk_mul_f32 v[22:23], v[22:23], v[142:143]
	v_pk_mul_f32 v[16:17], v[16:17], v[136:137]
	v_pk_mul_f32 v[18:19], v[18:19], v[138:139]
	s_nop 1
	v_permlane16_swap_b32_e32 v20, v16
	v_permlane16_swap_b32_e32 v21, v17
	v_permlane16_swap_b32_e32 v22, v18
	v_permlane16_swap_b32_e32 v23, v19
	s_nop 1
	v_permlane32_swap_b32_e32 v20, v16
	v_permlane32_swap_b32_e32 v21, v17
	v_permlane32_swap_b32_e32 v22, v18
	v_permlane32_swap_b32_e32 v23, v19
	s_nop 1
	global_store_dwordx4 v[196:197], v[20:23], off
	global_store_dwordx4 v[196:197], v[16:19], off offset:64
	v_pk_mul_f32 v[80:81], v[80:81], v[190:191] op_sel_hi:[1,0]
	v_pk_mul_f32 v[82:83], v[82:83], v[190:191] op_sel_hi:[1,0]
	v_pk_mul_f32 v[84:85], v[84:85], v[190:191] op_sel_hi:[1,0]
	v_pk_mul_f32 v[86:87], v[86:87], v[190:191] op_sel_hi:[1,0]
	v_pk_mul_f32 v[80:81], v[80:81], v[132:133]
	v_pk_mul_f32 v[82:83], v[82:83], v[134:135]
	v_pk_mul_f32 v[84:85], v[84:85], v[128:129]
	v_pk_mul_f32 v[86:87], v[86:87], v[130:131]
	s_nop 1
	v_permlane16_swap_b32_e32 v80, v84
	v_permlane16_swap_b32_e32 v81, v85
	v_permlane16_swap_b32_e32 v82, v86
	v_permlane16_swap_b32_e32 v83, v87
	s_nop 1
	v_permlane32_swap_b32_e32 v80, v84
	v_permlane32_swap_b32_e32 v81, v85
	v_permlane32_swap_b32_e32 v82, v86
	v_permlane32_swap_b32_e32 v83, v87
	s_nop 1
	global_store_dwordx4 v[196:197], v[80:83], off offset:512
	global_store_dwordx4 v[196:197], v[84:87], off offset:576
	v_add_co_u32_e32 v196, vcc, 0xb0000, v164
	v_addc_co_u32_e32 v197, vcc, 0, v165, vcc
	v_pk_mul_f32 v[4:5], v[4:5], v[192:193] op_sel_hi:[1,0]
	v_pk_mul_f32 v[6:7], v[6:7], v[192:193] op_sel_hi:[1,0]
	v_pk_mul_f32 v[0:1], v[0:1], v[192:193] op_sel_hi:[1,0]
	v_pk_mul_f32 v[2:3], v[2:3], v[192:193] op_sel_hi:[1,0]
	v_pk_mul_f32 v[4:5], v[4:5], v[140:141]
	v_pk_mul_f32 v[6:7], v[6:7], v[142:143]
	v_pk_mul_f32 v[0:1], v[0:1], v[136:137]
	v_pk_mul_f32 v[2:3], v[2:3], v[138:139]
	s_nop 1
	v_permlane16_swap_b32_e32 v4, v0
	v_permlane16_swap_b32_e32 v5, v1
	v_permlane16_swap_b32_e32 v6, v2
	v_permlane16_swap_b32_e32 v7, v3
	s_nop 1
	v_permlane32_swap_b32_e32 v4, v0
	v_permlane32_swap_b32_e32 v5, v1
	v_permlane32_swap_b32_e32 v6, v2
	v_permlane32_swap_b32_e32 v7, v3
	s_nop 1
	global_store_dwordx4 v[196:197], v[4:7], off
	global_store_dwordx4 v[196:197], v[0:3], off offset:64
	v_pk_mul_f32 v[56:57], v[56:57], v[192:193] op_sel_hi:[1,0]
	v_pk_mul_f32 v[58:59], v[58:59], v[192:193] op_sel_hi:[1,0]
	v_pk_mul_f32 v[60:61], v[60:61], v[192:193] op_sel_hi:[1,0]
	v_pk_mul_f32 v[62:63], v[62:63], v[192:193] op_sel_hi:[1,0]
	v_pk_mul_f32 v[56:57], v[56:57], v[132:133]
	v_pk_mul_f32 v[58:59], v[58:59], v[134:135]
	v_pk_mul_f32 v[60:61], v[60:61], v[128:129]
	v_pk_mul_f32 v[62:63], v[62:63], v[130:131]
	s_nop 1
	v_permlane16_swap_b32_e32 v56, v60
	v_permlane16_swap_b32_e32 v57, v61
	v_permlane16_swap_b32_e32 v58, v62
	v_permlane16_swap_b32_e32 v59, v63
	s_nop 1
	v_permlane32_swap_b32_e32 v56, v60
	v_permlane32_swap_b32_e32 v57, v61
	v_permlane32_swap_b32_e32 v58, v62
	v_permlane32_swap_b32_e32 v59, v63
	s_nop 1
	global_store_dwordx4 v[196:197], v[56:59], off offset:512
	global_store_dwordx4 v[196:197], v[60:63], off offset:576
	s_and_b64 vcc, exec, s[4:5]
	s_mov_b64 s[4:5], -1
	s_cbranch_vccnz .LBB0_1404
	s_nop 0
	v_lshl_add_u32 v0, s76, 8, v178
	v_or_b32_e32 v6, 16, v0
	v_lshl_or_b32 v2, s75, 8, v180
	v_ashrrev_i32_e32 v1, 31, v0
	v_ashrrev_i32_e32 v7, 31, v6
	v_ashrrev_i32_e32 v3, 31, v2
	v_lshlrev_b64 v[4:5], 11, v[0:1]
	v_lshlrev_b64 v[6:7], 11, v[6:7]
	v_lshl_add_u64 v[4:5], s[22:23], 0, v[4:5]
	v_lshlrev_b64 v[2:3], 1, v[2:3]
	v_lshl_add_u64 v[6:7], s[22:23], 0, v[6:7]
	v_lshl_add_u64 v[4:5], v[4:5], 0, v[2:3]
	v_lshl_add_u64 v[6:7], v[6:7], 0, v[2:3]
	global_load_dwordx4 v[60:63], v[4:5], off
	global_load_dwordx4 v[52:55], v[4:5], off offset:256
	global_load_dwordx4 v[56:59], v[6:7], off
	global_load_dwordx4 v[44:47], v[6:7], off offset:256
	v_or_b32_e32 v6, 32, v0
	v_or_b32_e32 v0, 48, v0
	v_ashrrev_i32_e32 v7, 31, v6
	v_ashrrev_i32_e32 v1, 31, v0
	v_lshlrev_b64 v[6:7], 11, v[6:7]
	v_lshlrev_b64 v[0:1], 11, v[0:1]
	v_lshl_add_u64 v[6:7], s[22:23], 0, v[6:7]
	v_lshl_add_u64 v[0:1], s[22:23], 0, v[0:1]
	v_lshl_add_u64 v[6:7], v[6:7], 0, v[2:3]
	v_lshl_add_u64 v[0:1], v[0:1], 0, v[2:3]
	v_add_co_u32_e32 v2, vcc, s56, v4
	global_load_dwordx4 v[48:51], v[6:7], off
	global_load_dwordx4 v[36:39], v[6:7], off offset:256
	v_addc_co_u32_e32 v3, vcc, 0, v5, vcc
	global_load_dwordx4 v[40:43], v[0:1], off
	global_load_dwordx4 v[32:35], v[0:1], off offset:256
	v_lshl_add_u64 v[0:1], v[4:5], 0, s[10:11]
	global_load_dwordx4 v[28:31], v[2:3], off
	global_load_dwordx4 v[24:27], v[0:1], off offset:256
	v_add_co_u32_e32 v2, vcc, s57, v4
	v_lshl_add_u64 v[0:1], v[4:5], 0, s[12:13]
	s_nop 0
	v_addc_co_u32_e32 v3, vcc, 0, v5, vcc
	global_load_dwordx4 v[20:23], v[2:3], off
	global_load_dwordx4 v[16:19], v[0:1], off offset:256
	v_add_co_u32_e32 v2, vcc, 0x50000, v4
	v_lshl_add_u64 v[0:1], v[4:5], 0, s[14:15]
	s_nop 0
	v_addc_co_u32_e32 v3, vcc, 0, v5, vcc
	global_load_dwordx4 v[12:15], v[2:3], off
	global_load_dwordx4 v[8:11], v[0:1], off offset:256
	v_add_co_u32_e32 v2, vcc, 0x58000, v4
	v_lshl_add_u64 v[0:1], v[4:5], 0, s[16:17]
	s_nop 0
	v_addc_co_u32_e32 v3, vcc, 0, v5, vcc
	global_load_dwordx4 v[4:7], v[2:3], off
	s_nop 0
	global_load_dwordx4 v[0:3], v[0:1], off offset:256
	s_andn2_b64 vcc, exec, s[20:21]
	s_cbranch_vccnz .LBB0_1403
	s_barrier
	s_branch .LBB0_1403
